# P1: PP tiles also prefetch next tile's first k-tile; first PP tile staged during last big tile's epilogue
# speedup vs baseline: 1.0672x; 1.0015x over previous
.LBB0_107:
	s_or_b64 exec, exec, s[4:5]
	s_add_u32 s60, s76, 0x3eda000
	s_addc_u32 s61, s77, 0
	s_cmpk_gt_i32 s59, 0x4a3
	s_waitcnt lgkmcnt(0)
	s_mov_b32 s96, 0
	s_barrier
	s_cbranch_scc1 .LBB0_120
	s_add_u32 s34, s76, 0x1180000
	s_addc_u32 s35, s77, 0
	v_mov_b32_e32 v131, 0
	s_mov_b64 s[4:5], 0x80
	s_mov_b64 s[6:7], 0x11c0080
	s_mov_b64 s[8:9], 0x100
	s_mov_b64 s[10:11], 0x1180100
	s_mov_b64 s[12:13], 0x40100
	s_mov_b64 s[14:15], 0x11c0100
	s_mov_b64 s[16:17], 0x180
	s_mov_b64 s[18:19], 0x1180180
	s_mov_b64 s[20:21], 0x40180
	s_movk_i32 s36, 0x2400
	v_mov_b32_e32 v144, 1
	s_mov_b32 s96, 0
	s_mov_b32 s37, s59
	s_branch .LBB0_110

.Lp1pf_last:
	s_mov_b32 s96, 0
	s_cmpk_lg_i32 s58, 0x100
	s_cbranch_scc1 .Lp1pf_dummy
	s_sub_i32 s26, s59, 0xa4
	s_cmp_lt_i32 s26, 0
	s_cbranch_scc1 .Lp1pf_dummy
	s_mov_b32 s96, 1
	v_lshrrev_b32_e32 v247, 11, v243
	v_and_b32_e32 v243, 0x7ff, v243
	v_lshl_or_b32 v243, v247, 9, v243
	v_lshrrev_b32_e32 v247, 11, v244
	v_and_b32_e32 v244, 0x7ff, v244
	v_lshl_or_b32 v244, v247, 9, v244
	v_lshrrev_b32_e32 v247, 11, v245
	v_and_b32_e32 v245, 0x7ff, v245
	v_lshl_or_b32 v245, v247, 9, v245
	v_lshrrev_b32_e32 v247, 11, v246
	v_and_b32_e32 v246, 0x7ff, v246
	v_lshl_or_b32 v246, v247, 9, v246
	s_and_b32 s27, s26, 7
	s_lshr_b32 s26, s26, 3
	s_mul_i32 s27, s27, 33
	s_add_i32 s26, s26, s27
	s_lshr_b32 s27, s26, 5
	s_and_b32 s26, s26, 31
	s_cmp_lt_u32 s27, 8
	s_cselect_b32 s28, 3, 1
	s_cselect_b32 s29, 7, 1
	s_lshr_b32 s30, s26, s28
	s_and_b32 s26, s26, s29
	s_lshl_b32 s27, s27, 3
	s_add_i32 s26, s26, s27
	s_lshl_b32 s26, s26, 17
	s_lshl_b32 s28, s30, 17
	s_add_u32 s26, s0, s26
	s_addc_u32 s27, s1, 0
	s_add_u32 s28, s28, 0x1100000
	s_add_u32 s28, s76, s28
	s_addc_u32 s29, s77, 0
	s_add_u32 s42, s28, 0x10000
	s_addc_u32 s43, s29, 0
	s_add_u32 s50, s26, 0x10000
	s_addc_u32 s51, s27, 0
	s_add_i32 m0, s40, 0x10000
	s_nop 0
	global_load_lds_dwordx4 v243, s[28:29]
	s_add_i32 m0, s40, 0x12000
	s_nop 0
	global_load_lds_dwordx4 v244, s[28:29]
	s_add_i32 m0, s40, 0
	s_nop 0
	global_load_lds_dwordx4 v245, s[26:27]
	s_add_i32 m0, s40, 0x2000
	s_nop 0
	global_load_lds_dwordx4 v246, s[26:27]
	s_add_i32 m0, s40, 0x14000
	s_nop 0
	global_load_lds_dwordx4 v243, s[42:43]
	s_add_i32 m0, s40, 0x16000
	s_nop 0
	global_load_lds_dwordx4 v244, s[42:43]
	s_add_i32 m0, s40, 0x4000
	s_nop 0
	global_load_lds_dwordx4 v245, s[50:51]
	s_add_i32 m0, s40, 0x6000
	s_nop 0
	global_load_lds_dwordx4 v246, s[50:51]
	s_branch .Lp1pf_done

.Lpp_keep:
	s_cmpk_gt_i32 s18, 0x107
	s_cbranch_scc1 .LBB0_127
	s_add_u32 s19, s76, 0x1100000
	s_addc_u32 s20, s77, 0
	s_add_u32 s2, s76, 0xd35a000
	s_addc_u32 s3, s77, 0
	s_mov_b32 s21, 0x7fffe0
	v_mov_b32_e32 v131, 0
	s_add_i32 s22, 0, 0x18000
	s_mov_b64 s[4:5], 0x80
	s_add_i32 s23, 0, 0x1c000
	s_mov_b64 s[6:7], 0x100
	s_mov_b64 s[8:9], 0x180
	v_mov_b32_e32 v134, 1
	s_add_i32 s24, 0, 0x10000
	s_add_i32 s25, 0, 0x14000
	s_branch .LBB0_123
.LBB0_122:
	s_lshl_b32 s13, s26, 6
	v_or_b32_e32 v130, s12, v132
	v_add_u32_e32 v132, s13, v130
	v_or_b32_e32 v130, s10, v133
	v_or_b32_e32 v136, s11, v130
	v_or_b32_e32 v138, 16, v132
	v_ashrrev_i32_e32 v133, 31, v132
	v_ashrrev_i32_e32 v139, 31, v138
	s_add_i32 s14, s18, s97
	s_mov_b32 s96, 0
	s_cmpk_gt_i32 s14, 0x107
	s_cbranch_scc1 .Lpppf_skip
	s_mov_b32 s96, 1
	s_and_b32 s15, s14, 7
	s_lshr_b32 s14, s14, 3
	s_mul_i32 s15, s15, 33
	s_add_i32 s14, s14, s15
	s_lshr_b32 s15, s14, 5
	s_and_b32 s14, s14, 31
	s_cmp_lt_u32 s15, 8
	s_cselect_b32 s16, 3, 1
	s_cselect_b32 s17, 7, 1
	s_lshr_b32 s16, s14, s16
	s_and_b32 s14, s14, s17
	s_lshl_b32 s15, s15, 3
	s_add_i32 s14, s14, s15
	s_lshl_b32 s14, s14, 17
	s_lshl_b32 s16, s16, 17
	s_add_u32 s14, s0, s14
	s_addc_u32 s15, s1, 0
	s_add_u32 s16, s19, s16
	s_addc_u32 s17, s20, 0
	s_add_u32 s30, s16, 0x10000
	s_addc_u32 s31, s17, 0
	s_add_u32 s28, s14, 0x10000
	s_addc_u32 s29, s15, 0
	v_readfirstlane_b32 s27, v0
	s_lshr_b32 s27, s27, 6
	s_lshl_b32 s27, s27, 10
	s_add_i32 m0, s27, 0x10000
	s_nop 0
	global_load_lds_dwordx4 v243, s[16:17]
	s_add_i32 m0, s27, 0x12000
	s_nop 0
	global_load_lds_dwordx4 v244, s[16:17]
	s_add_i32 m0, s27, 0
	s_nop 0
	global_load_lds_dwordx4 v245, s[14:15]
	s_add_i32 m0, s27, 0x2000
	s_nop 0
	global_load_lds_dwordx4 v246, s[14:15]
	s_add_i32 m0, s27, 0x14000
	s_nop 0
	global_load_lds_dwordx4 v243, s[30:31]
	s_add_i32 m0, s27, 0x16000
	s_nop 0
	global_load_lds_dwordx4 v244, s[30:31]
	s_add_i32 m0, s27, 0x4000
	s_nop 0
	global_load_lds_dwordx4 v245, s[28:29]
	s_add_i32 m0, s27, 0x6000
	s_nop 0
	global_load_lds_dwordx4 v246, s[28:29]
.Lpppf_skip:
	v_cvt_pk_bf16_f32 v122, v122, v123
	v_cvt_pk_bf16_f32 v123, v124, v125
	v_cvt_pk_bf16_f32 v124, v114, v115
	v_lshlrev_b64 v[114:115], 11, v[132:133]
	v_ashrrev_i32_e32 v137, 31, v136
	v_cvt_pk_bf16_f32 v125, v116, v117
	v_lshl_add_u64 v[116:117], s[2:3], 0, v[114:115]
	v_lshlrev_b64 v[114:115], 1, v[136:137]
	v_cvt_pk_bf16_f32 v102, v102, v103
	v_cvt_pk_bf16_f32 v103, v104, v105
	v_cvt_pk_bf16_f32 v104, v98, v99
	v_lshlrev_b64 v[98:99], 11, v[138:139]
	v_lshl_add_u64 v[136:137], v[116:117], 0, v[114:115]
	v_cvt_pk_bf16_f32 v116, v126, v127
	v_cvt_pk_bf16_f32 v117, v128, v129
	v_lshl_add_u64 v[98:99], s[2:3], 0, v[98:99]
	v_cvt_pk_bf16_f32 v118, v118, v119
	v_cvt_pk_bf16_f32 v119, v120, v121
	global_store_dwordx4 v[136:137], v[116:119], off offset:256
	v_cvt_pk_bf16_f32 v105, v100, v101
	v_cvt_pk_bf16_f32 v100, v106, v107
	v_cvt_pk_bf16_f32 v101, v108, v109
	v_cvt_pk_bf16_f32 v86, v86, v87
	v_cvt_pk_bf16_f32 v87, v88, v89
	s_nop 1
	v_lshl_add_u64 v[116:117], v[98:99], 0, v[114:115]
	v_cvt_pk_bf16_f32 v98, v110, v111
	v_cvt_pk_bf16_f32 v99, v112, v113
	global_store_dwordx4 v[116:117], v[98:101], off offset:256
	v_cvt_pk_bf16_f32 v88, v82, v83
	v_cvt_pk_bf16_f32 v70, v70, v71
	v_cvt_pk_bf16_f32 v71, v72, v73
	v_cvt_pk_bf16_f32 v72, v58, v59
	v_cvt_pk_bf16_f32 v89, v84, v85
	s_nop 1
	v_or_b32_e32 v100, 32, v132
	v_or_b32_e32 v98, 48, v132
	v_ashrrev_i32_e32 v101, 31, v100
	v_ashrrev_i32_e32 v99, 31, v98
	v_lshlrev_b64 v[82:83], 11, v[100:101]
	v_lshl_add_u64 v[82:83], s[2:3], 0, v[82:83]
	v_lshlrev_b64 v[58:59], 11, v[98:99]
	v_lshl_add_u64 v[100:101], v[82:83], 0, v[114:115]
	v_cvt_pk_bf16_f32 v82, v94, v95
	v_cvt_pk_bf16_f32 v83, v96, v97
	v_lshl_add_u64 v[58:59], s[2:3], 0, v[58:59]
	v_cvt_pk_bf16_f32 v84, v90, v91
	v_cvt_pk_bf16_f32 v85, v92, v93
	global_store_dwordx4 v[100:101], v[82:85], off offset:256
	v_cvt_pk_bf16_f32 v73, v60, v61
	v_cvt_pk_bf16_f32 v46, v46, v47
	v_cvt_pk_bf16_f32 v47, v48, v49
	v_cvt_pk_bf16_f32 v49, v40, v41
	v_cvt_pk_bf16_f32 v40, v34, v35
	s_nop 1
	v_lshl_add_u64 v[82:83], v[58:59], 0, v[114:115]
	global_store_dwordx4 v[82:83], v[70:73], off
	v_cvt_pk_bf16_f32 v41, v36, v37
	v_add_u32_e32 v34, 0xb0, v132
	v_add_u32_e32 v36, 0xa0, v132
	v_add_u32_e32 v70, 0x80, v132
	v_add_u32_e32 v72, 0x90, v132
	v_cvt_pk_bf16_f32 v60, v74, v75
	v_ashrrev_i32_e32 v73, 31, v72
	v_ashrrev_i32_e32 v71, 31, v70
	v_ashrrev_i32_e32 v35, 31, v34
	v_ashrrev_i32_e32 v37, 31, v36
	v_cvt_pk_bf16_f32 v58, v78, v79
	v_cvt_pk_bf16_f32 v59, v80, v81
	v_cvt_pk_bf16_f32 v61, v76, v77
	global_store_dwordx4 v[82:83], v[58:61], off offset:256
	v_cvt_pk_bf16_f32 v48, v38, v39
	v_lshlrev_b64 v[38:39], 11, v[72:73]
	v_cvt_pk_bf16_f32 v30, v30, v31
	v_cvt_pk_bf16_f32 v31, v32, v33
	v_cvt_pk_bf16_f32 v32, v22, v23
	s_nop 0
	v_cvt_pk_bf16_f32 v60, v54, v55
	v_lshlrev_b64 v[54:55], 11, v[70:71]
	v_lshlrev_b64 v[22:23], 11, v[36:37]
	v_cvt_pk_bf16_f32 v14, v14, v15
	v_cvt_pk_bf16_f32 v15, v16, v17
	v_cvt_pk_bf16_f32 v16, v6, v7
	v_lshlrev_b64 v[6:7], 11, v[34:35]
	v_lshl_add_u64 v[54:55], s[2:3], 0, v[54:55]
	v_lshl_add_u64 v[38:39], s[2:3], 0, v[38:39]
	v_lshl_add_u64 v[22:23], s[2:3], 0, v[22:23]
	v_lshl_add_u64 v[6:7], s[2:3], 0, v[6:7]
	s_add_i32 s18, s18, s97
	v_cvt_pk_bf16_f32 v58, v66, v67
	v_cvt_pk_bf16_f32 v61, v56, v57
	v_lshl_add_u64 v[66:67], v[54:55], 0, v[114:115]
	v_cvt_pk_bf16_f32 v56, v50, v51
	v_lshl_add_u64 v[50:51], v[38:39], 0, v[114:115]
	v_cvt_pk_bf16_f32 v33, v24, v25
	v_lshl_add_u64 v[36:37], v[22:23], 0, v[114:115]
	v_cvt_pk_bf16_f32 v24, v18, v19
	v_lshl_add_u64 v[18:19], v[6:7], 0, v[114:115]
	s_cmpk_gt_i32 s18, 0x107
	global_store_dwordx4 v[136:137], v[122:125], off
	global_store_dwordx4 v[116:117], v[102:105], off
	global_store_dwordx4 v[100:101], v[86:89], off
	v_cvt_pk_bf16_f32 v59, v68, v69
	global_store_dwordx4 v[66:67], v[58:61], off
	v_cvt_pk_bf16_f32 v54, v62, v63
	v_cvt_pk_bf16_f32 v55, v64, v65
	v_cvt_pk_bf16_f32 v57, v52, v53
	global_store_dwordx4 v[66:67], v[54:57], off offset:256
	global_store_dwordx4 v[50:51], v[46:49], off
	v_cvt_pk_bf16_f32 v38, v42, v43
	v_cvt_pk_bf16_f32 v39, v44, v45
	global_store_dwordx4 v[50:51], v[38:41], off offset:256
	global_store_dwordx4 v[36:37], v[30:33], off
	v_cvt_pk_bf16_f32 v22, v26, v27
	v_cvt_pk_bf16_f32 v23, v28, v29
	v_cvt_pk_bf16_f32 v25, v20, v21
	global_store_dwordx4 v[36:37], v[22:25], off offset:256
	v_cvt_pk_bf16_f32 v17, v8, v9
	global_store_dwordx4 v[18:19], v[14:17], off
	v_cvt_pk_bf16_f32 v6, v10, v11
	v_cvt_pk_bf16_f32 v7, v12, v13
	v_cvt_pk_bf16_f32 v8, v2, v3
	v_cvt_pk_bf16_f32 v9, v4, v5
	global_store_dwordx4 v[18:19], v[6:9], off offset:256
	s_barrier
	s_cbranch_scc1 .LBB0_127
.LBB0_123:
	s_ashr_i32 s10, s18, 31
	s_lshr_b32 s10, s10, 29
	s_add_i32 s10, s18, s10
	s_ashr_i32 s11, s10, 3
	s_and_b32 s10, s10, -8
	s_sub_i32 s10, s18, s10
	s_cmp_lt_i32 s10, 0
	s_cselect_b32 s12, 34, 33
	s_mul_i32 s10, s10, s12
	s_add_i32 s10, s10, s11
	s_ashr_i32 s11, s10, 31
	s_lshr_b32 s11, s11, 27
	s_add_i32 s11, s10, s11
	s_ashr_i32 s12, s11, 5
	s_lshl_b32 s12, s12, 3
	s_sub_i32 s13, 0x42, s12
	s_min_u32 s13, s13, 8
	s_andn2_b32 s11, s11, 31
	s_sub_i32 s14, s10, s11
	v_cvt_f32_ubyte0_e32 v3, s13
	v_cvt_f32_i32_e32 v2, s14
	v_rcp_iflag_f32_e32 v4, v3
	s_ashr_i32 s10, s14, 30
	s_or_b32 s15, s10, 1
	v_mov_b32_e32 v16, v0
	v_mul_f32_e32 v4, v2, v4
	v_trunc_f32_e32 v4, v4
	v_fma_f32 v2, -v4, v3, v2
	v_cvt_i32_f32_e32 v4, v4
	v_cmp_ge_f32_e64 s[10:11], |v2|, v3
	s_and_b64 s[10:11], s[10:11], exec
	v_readfirstlane_b32 s11, v4
	v_bfe_i32 v4, v16, 27, 1
	v_lshlrev_b32_e32 v3, 4, v16
	v_lshrrev_b32_e32 v4, 22, v4
	v_add_u32_e32 v4, v3, v4
	v_and_b32_e32 v4, 0xfffffc00, v4
	v_sub_u32_e32 v4, v3, v4
	v_ashrrev_i32_e32 v2, 31, v16
	v_lshrrev_b32_e32 v5, 4, v4
	v_lshrrev_b32_e32 v2, 26, v2
	v_bitop3_b32 v5, v5, v4, 32 bitop3:0x6c
	v_ashrrev_i32_e32 v4, 31, v4
	v_add_u32_e32 v2, v16, v2
	v_lshrrev_b32_e32 v4, 26, v4
	v_ashrrev_i32_e32 v2, 6, v2
	v_add_u32_e32 v4, v5, v4
	v_lshlrev_b32_e32 v6, 3, v2
	v_ashrrev_i32_e32 v4, 6, v4
	v_and_b32_e32 v6, -16, v6
	v_mul_i32_i24_e32 v7, 64, v4
	v_add_u32_e32 v6, v4, v6
	v_sub_u32_e32 v5, v5, v7
	v_lshlrev_b32_e32 v2, 5, v2
	v_ashrrev_i16_sdwa v5, v134, sext(v5) dst_sel:DWORD dst_unused:UNUSED_PAD src0_sel:DWORD src1_sel:BYTE_0
	v_lshlrev_b32_e32 v7, 1, v6
	v_lshrrev_b32_e32 v8, 2, v6
	v_and_b32_e32 v4, 3, v4
	v_and_b32_e32 v2, 32, v2
	v_bfe_i32 v5, v5, 0, 16
	v_and_b32_e32 v7, 24, v7
	v_and_b32_e32 v8, 4, v8
	v_and_or_b32 v4, v6, s21, v4
	v_or3_b32 v4, v4, v7, v8
	v_add_lshl_u32 v5, v2, v5, 1
	v_add_u32_e32 v3, 0x2000, v3
	v_lshl_add_u32 v130, v4, 9, v5
	v_ashrrev_i32_e32 v4, 31, v3
	v_lshrrev_b32_e32 v4, 22, v4
	v_add_u32_e32 v4, v3, v4
	s_cselect_b32 s10, s15, 0
	v_ashrrev_i32_e32 v4, 10, v4
	s_add_i32 s10, s11, s10
	v_lshl_add_u32 v2, v6, 9, v5
	v_mul_i32_i24_e32 v5, 0x400, v4
	s_sext_i32_i8 s11, s10
	s_mul_i32 s10, s10, s13
	v_sub_u32_e32 v3, v3, v5
	s_sub_i32 s10, s14, s10
	v_lshrrev_b32_e32 v5, 4, v3
	s_sext_i32_i8 s10, s10
	v_bitop3_b32 v3, v5, v3, 32 bitop3:0x6c
	s_add_i32 s12, s12, s10
	v_ashrrev_i32_e32 v6, 31, v3
	s_lshl_b32 s12, s12, 8
	s_lshl_b32 s10, s11, 8
	v_readfirstlane_b32 s27, v16
	v_lshrrev_b32_e32 v6, 26, v6
	v_lshlrev_b32_e32 v5, 3, v4
	v_add_u32_e32 v6, v3, v6
	s_ashr_i32 s28, s27, 6
	s_ashr_i32 s13, s12, 31
	s_ashr_i32 s11, s10, 31
	s_ashr_i32 s26, s27, 8
	v_and_b32_e32 v5, -16, v5
	v_ashrrev_i32_e32 v7, 6, v6
	v_and_b32_e32 v6, 0xc0, v6
	s_lshl_b32 s35, s28, 10
	s_lshl_b64 s[14:15], s[12:13], 9
	s_lshl_b64 s[16:17], s[10:11], 9
	v_add_u32_e32 v5, v7, v5
	v_sub_u32_e32 v3, v3, v6
	s_add_u32 s16, s19, s16
	v_lshlrev_b32_e32 v4, 5, v4
	v_ashrrev_i16_sdwa v3, v134, sext(v3) dst_sel:DWORD dst_unused:UNUSED_PAD src0_sel:DWORD src1_sel:BYTE_0
	v_lshlrev_b32_e32 v6, 1, v5
	v_lshrrev_b32_e32 v8, 2, v5
	v_and_b32_e32 v7, 3, v7
	s_addc_u32 s17, s20, s17
	s_add_i32 s40, s35, 0
	v_and_b32_e32 v4, 32, v4
	v_bfe_i32 v3, v3, 0, 16
	v_and_b32_e32 v6, 24, v6
	v_and_b32_e32 v8, 4, v8
	v_and_or_b32 v7, v5, s21, v7
	s_add_i32 m0, s40, 0x10000
	v_or3_b32 v6, v7, v6, v8
	v_add_lshl_u32 v3, v4, v3, 1
	s_add_i32 m0, s40, 0x12000
	v_lshl_add_u32 v6, v6, 9, v3
	s_add_u32 s14, s0, s14
	s_addc_u32 s15, s1, s15
	s_mov_b32 m0, s40
	s_add_i32 s41, s40, 0x2000
	v_lshl_add_u32 v4, v5, 9, v3
	s_mov_b32 m0, s41
	s_add_u32 s30, s16, 0x10000
	s_addc_u32 s31, s17, 0
	s_add_i32 m0, s40, 0x14000
	v_mov_b32_e32 v7, v131
	s_add_i32 m0, s40, 0x16000
	v_mov_b32_e32 v3, v131
	s_add_u32 s30, s14, 0x10000
	s_addc_u32 s31, s15, 0
	s_add_i32 s39, s40, 0x4000
	s_mov_b32 m0, s39
	s_add_i32 s36, s40, 0x6000
	s_mov_b32 m0, s36
	v_mov_b32_e32 v5, v131
	v_mov_b32_e32 v243, v130
	v_mov_b32_e32 v244, v6
	v_mov_b32_e32 v245, v2
	v_mov_b32_e32 v246, v4
	s_cmp_eq_u32 s96, 1
	s_cbranch_scc1 .Lpppf_have
	s_add_u32 s30, s16, 0x10000
	s_addc_u32 s31, s17, 0
	s_add_i32 m0, s40, 0x10000
	s_nop 0
	global_load_lds_dwordx4 v130, s[16:17]
	s_add_i32 m0, s40, 0x12000
	s_nop 0
	global_load_lds_dwordx4 v6, s[16:17]
	s_add_i32 m0, s40, 0
	s_nop 0
	global_load_lds_dwordx4 v2, s[14:15]
	s_add_i32 m0, s40, 0x2000
	s_nop 0
	global_load_lds_dwordx4 v4, s[14:15]
	s_add_i32 m0, s40, 0x14000
	s_nop 0
	global_load_lds_dwordx4 v130, s[30:31]
	s_add_i32 m0, s40, 0x16000
	s_nop 0
	global_load_lds_dwordx4 v6, s[30:31]
	s_add_u32 s30, s14, 0x10000
	s_addc_u32 s31, s15, 0
	s_add_i32 m0, s40, 0x4000
	s_nop 0
	global_load_lds_dwordx4 v2, s[30:31]
	s_add_i32 m0, s40, 0x6000
	s_nop 0
	global_load_lds_dwordx4 v4, s[30:31]
	s_waitcnt vmcnt(4)
	s_branch .Lpppf_join

.Lpppf_join:
	v_lshl_add_u64 v[14:15], s[16:17], 0, v[130:131]
	v_lshl_add_u64 v[12:13], s[16:17], 0, v[6:7]
	v_lshl_add_u64 v[8:9], s[14:15], 0, v[2:3]
	s_cmp_lg_u32 s26, 1
	v_lshl_add_u64 v[10:11], s[14:15], 0, v[4:5]
	s_cbranch_scc1 .LBB0_125
	s_barrier
.LBB0_125:
	s_lshl_b32 s11, s28, 5
	s_add_i32 s38, s22, s35
	s_and_b32 s11, s11, 0x60
	v_lshl_add_u64 v[18:19], v[14:15], 0, s[4:5]
	s_mov_b32 m0, s38
	s_add_i32 s37, s38, 0x2000
	s_lshl_b32 s28, s26, 13
	s_lshl_b32 s30, s11, 7
	s_barrier
	global_load_lds_dwordx4 v[18:19], off
	v_lshl_add_u64 v[18:19], v[12:13], 0, s[4:5]
	s_mov_b32 m0, s37
	s_add_i32 s34, s40, 0x8000
	s_add_i32 s31, s40, 0xa000
	global_load_lds_dwordx4 v[18:19], off
	v_lshl_add_u64 v[18:19], v[8:9], 0, s[4:5]
	s_mov_b32 m0, s34
	s_add_u32 s42, s16, 0x10080
	global_load_lds_dwordx4 v[18:19], off
	v_lshl_add_u64 v[18:19], v[10:11], 0, s[4:5]
	s_mov_b32 m0, s31
	s_addc_u32 s43, s17, 0
	s_add_i32 s29, s23, s35
	global_load_lds_dwordx4 v[18:19], off
	v_lshl_add_u64 v[18:19], s[42:43], 0, v[130:131]
	s_mov_b32 m0, s29
	s_add_i32 s13, s29, 0x2000
	global_load_lds_dwordx4 v[18:19], off
	v_lshl_add_u64 v[18:19], s[42:43], 0, v[6:7]
	s_mov_b32 m0, s13
	v_lshrrev_b32_e32 v17, 1, v16
	global_load_lds_dwordx4 v[18:19], off
	v_and_b32_e32 v133, 24, v17
	v_and_b32_e32 v132, 15, v16
	v_lshlrev_b32_e32 v17, 1, v133
	v_lshlrev_b32_e32 v16, 2, v16
	v_lshl_or_b32 v17, v132, 6, v17
	v_and_b32_e32 v16, 32, v16
	v_bitop3_b32 v32, v17, s30, v16 bitop3:0xde
	v_add_u32_e32 v135, s24, v32
	v_bitop3_b32 v33, v17, s28, v16 bitop3:0xde
	s_waitcnt vmcnt(6)
	s_barrier
	ds_read_b128 v[16:19], v135
	ds_read_b128 v[20:23], v135 offset:1024
	ds_read_b128 v[24:27], v135 offset:2048
	ds_read_b128 v[28:31], v135 offset:3072
	v_add_u32_e32 v240, 0, v33
	v_add_u32_e32 v216, s25, v32
	v_add_u32_e32 v217, s22, v32
	v_add_u32_e32 v236, s23, v32
	s_add_u32 s42, s14, 0x10080
	s_addc_u32 s43, s15, 0
	s_add_i32 s30, s40, 0xc000
	v_lshl_add_u64 v[64:65], s[42:43], 0, v[2:3]
	s_mov_b32 m0, s30
	s_add_i32 s28, s40, 0xe000
	ds_read_b128 v[32:35], v240
	ds_read_b128 v[36:39], v240 offset:1024
	ds_read_b128 v[40:43], v240 offset:2048
	ds_read_b128 v[44:47], v240 offset:3072
	ds_read_b128 v[48:51], v240 offset:4096
	ds_read_b128 v[52:55], v240 offset:5120
	ds_read_b128 v[56:59], v240 offset:6144
	ds_read_b128 v[60:63], v240 offset:7168
	global_load_lds_dwordx4 v[64:65], off
	v_lshl_add_u64 v[64:65], s[42:43], 0, v[4:5]
	s_mov_b32 m0, s28
	s_nop 0
	global_load_lds_dwordx4 v[64:65], off
	s_waitcnt lgkmcnt(8)
	s_barrier
	s_waitcnt lgkmcnt(0)
	s_setprio 1
	s_waitcnt lgkmcnt(0)
	v_mfma_f32_16x16x32_bf16 v[64:67], v[16:19], v[32:35], 0
	v_mfma_f32_16x16x32_bf16 v[68:71], v[24:27], v[32:35], 0
	v_mfma_f32_16x16x32_bf16 v[72:75], v[16:19], v[40:43], 0
	v_mfma_f32_16x16x32_bf16 v[76:79], v[24:27], v[40:43], 0
	v_mfma_f32_16x16x32_bf16 v[80:83], v[16:19], v[48:51], 0
	v_mfma_f32_16x16x32_bf16 v[84:87], v[24:27], v[48:51], 0
	v_mfma_f32_16x16x32_bf16 v[88:91], v[16:19], v[56:59], 0
	v_mfma_f32_16x16x32_bf16 v[92:95], v[24:27], v[56:59], 0
	v_mfma_f32_16x16x32_bf16 v[64:67], v[20:23], v[36:39], v[64:67]
	v_mfma_f32_16x16x32_bf16 v[68:71], v[28:31], v[36:39], v[68:71]
	v_mfma_f32_16x16x32_bf16 v[72:75], v[20:23], v[44:47], v[72:75]
	v_mfma_f32_16x16x32_bf16 v[76:79], v[28:31], v[44:47], v[76:79]
	v_mfma_f32_16x16x32_bf16 v[80:83], v[20:23], v[52:55], v[80:83]
	v_mfma_f32_16x16x32_bf16 v[84:87], v[28:31], v[52:55], v[84:87]
	v_mfma_f32_16x16x32_bf16 v[88:91], v[20:23], v[60:63], v[88:91]
	v_mfma_f32_16x16x32_bf16 v[92:95], v[28:31], v[60:63], v[92:95]
	s_setprio 0
	s_barrier
	s_add_i32 s42, s24, s35
	v_lshl_add_u64 v[112:113], v[14:15], 0, s[6:7]
	s_mov_b32 m0, s42
	ds_read_b128 v[96:99], v216
	ds_read_b128 v[100:103], v216 offset:1024
	ds_read_b128 v[104:107], v216 offset:2048
	ds_read_b128 v[108:111], v216 offset:3072
	global_load_lds_dwordx4 v[112:113], off
	v_lshl_add_u64 v[112:113], v[12:13], 0, s[6:7]
	s_add_i32 m0, s42, 0x2000
	s_nop 0
	global_load_lds_dwordx4 v[112:113], off
	s_barrier
	s_waitcnt lgkmcnt(0)
	s_setprio 1
	s_waitcnt lgkmcnt(0)
	v_mfma_f32_16x16x32_bf16 v[112:115], v[96:99], v[32:35], 0
	v_mfma_f32_16x16x32_bf16 v[32:35], v[104:107], v[32:35], 0
	v_mfma_f32_16x16x32_bf16 v[112:115], v[100:103], v[36:39], v[112:115]
	v_mfma_f32_16x16x32_bf16 v[32:35], v[108:111], v[36:39], v[32:35]
	v_mfma_f32_16x16x32_bf16 v[36:39], v[96:99], v[40:43], 0
	v_mfma_f32_16x16x32_bf16 v[40:43], v[104:107], v[40:43], 0
	v_mfma_f32_16x16x32_bf16 v[36:39], v[100:103], v[44:47], v[36:39]
	v_mfma_f32_16x16x32_bf16 v[40:43], v[108:111], v[44:47], v[40:43]
	v_mfma_f32_16x16x32_bf16 v[44:47], v[96:99], v[48:51], 0
	v_mfma_f32_16x16x32_bf16 v[48:51], v[104:107], v[48:51], 0
	v_mfma_f32_16x16x32_bf16 v[44:47], v[100:103], v[52:55], v[44:47]
	v_mfma_f32_16x16x32_bf16 v[48:51], v[108:111], v[52:55], v[48:51]
	v_mfma_f32_16x16x32_bf16 v[52:55], v[96:99], v[56:59], 0
	v_mfma_f32_16x16x32_bf16 v[56:59], v[104:107], v[56:59], 0
	v_mfma_f32_16x16x32_bf16 v[52:55], v[100:103], v[60:63], v[52:55]
	v_mfma_f32_16x16x32_bf16 v[56:59], v[108:111], v[60:63], v[56:59]
	s_setprio 0
	s_mov_b32 m0, s40
	v_lshl_add_u64 v[128:129], v[8:9], 0, s[6:7]
	s_barrier
	ds_read_b128 v[60:63], v240 offset:16384
	ds_read_b128 v[116:119], v240 offset:17408
	ds_read_b128 v[120:123], v240 offset:18432
	ds_read_b128 v[124:127], v240 offset:19456
	ds_read_b128 v[136:139], v240 offset:20480
	ds_read_b128 v[140:143], v240 offset:21504
	ds_read_b128 v[144:147], v240 offset:22528
	ds_read_b128 v[148:151], v240 offset:23552
	global_load_lds_dwordx4 v[128:129], off
	v_lshl_add_u64 v[128:129], v[10:11], 0, s[6:7]
	s_mov_b32 m0, s41
	s_nop 0
	global_load_lds_dwordx4 v[128:129], off
	s_barrier
	s_waitcnt lgkmcnt(0)
	s_setprio 1
	s_waitcnt lgkmcnt(0)
	v_mfma_f32_16x16x32_bf16 v[152:155], v[16:19], v[60:63], 0
	v_mfma_f32_16x16x32_bf16 v[160:163], v[16:19], v[120:123], 0
	v_mfma_f32_16x16x32_bf16 v[168:171], v[16:19], v[136:139], 0
	v_mfma_f32_16x16x32_bf16 v[16:19], v[16:19], v[144:147], 0
	v_mfma_f32_16x16x32_bf16 v[152:155], v[20:23], v[116:119], v[152:155]
	v_mfma_f32_16x16x32_bf16 v[160:163], v[20:23], v[124:127], v[160:163]
	v_mfma_f32_16x16x32_bf16 v[168:171], v[20:23], v[140:143], v[168:171]
	v_mfma_f32_16x16x32_bf16 v[16:19], v[20:23], v[148:151], v[16:19]
	v_mfma_f32_16x16x32_bf16 v[20:23], v[24:27], v[144:147], 0
	v_mfma_f32_16x16x32_bf16 v[156:159], v[24:27], v[60:63], 0
	v_mfma_f32_16x16x32_bf16 v[164:167], v[24:27], v[120:123], 0
	v_mfma_f32_16x16x32_bf16 v[172:175], v[24:27], v[136:139], 0
	v_mfma_f32_16x16x32_bf16 v[20:23], v[28:31], v[148:151], v[20:23]
	v_mfma_f32_16x16x32_bf16 v[156:159], v[28:31], v[116:119], v[156:159]
	v_mfma_f32_16x16x32_bf16 v[164:167], v[28:31], v[124:127], v[164:167]
	v_mfma_f32_16x16x32_bf16 v[172:175], v[28:31], v[140:143], v[172:175]
	s_setprio 0
	s_barrier
	s_add_u32 s40, s16, 0x10100
	s_addc_u32 s41, s17, 0
	s_add_i32 s35, s25, s35
	v_lshl_add_u64 v[24:25], s[40:41], 0, v[130:131]
	s_mov_b32 m0, s35
	s_nop 0
	global_load_lds_dwordx4 v[24:25], off
	v_lshl_add_u64 v[24:25], s[40:41], 0, v[6:7]
	s_add_i32 m0, s35, 0x2000
	s_nop 0
	global_load_lds_dwordx4 v[24:25], off
	s_waitcnt vmcnt(6)
	s_barrier
	s_setprio 1
	v_mfma_f32_16x16x32_bf16 v[24:27], v[96:99], v[60:63], 0
	v_mfma_f32_16x16x32_bf16 v[28:31], v[104:107], v[60:63], 0
	v_mfma_f32_16x16x32_bf16 v[24:27], v[100:103], v[116:119], v[24:27]
	v_mfma_f32_16x16x32_bf16 v[28:31], v[108:111], v[116:119], v[28:31]
	v_mfma_f32_16x16x32_bf16 v[60:63], v[96:99], v[120:123], 0
	v_mfma_f32_16x16x32_bf16 v[116:119], v[104:107], v[120:123], 0
	v_mfma_f32_16x16x32_bf16 v[120:123], v[96:99], v[136:139], 0
	v_mfma_f32_16x16x32_bf16 v[96:99], v[96:99], v[144:147], 0
	v_mfma_f32_16x16x32_bf16 v[60:63], v[100:103], v[124:127], v[60:63]
	v_mfma_f32_16x16x32_bf16 v[116:119], v[108:111], v[124:127], v[116:119]
	v_mfma_f32_16x16x32_bf16 v[120:123], v[100:103], v[140:143], v[120:123]
	v_mfma_f32_16x16x32_bf16 v[124:127], v[104:107], v[136:139], 0
	v_mfma_f32_16x16x32_bf16 v[96:99], v[100:103], v[148:151], v[96:99]
	v_mfma_f32_16x16x32_bf16 v[100:103], v[104:107], v[144:147], 0
	v_mfma_f32_16x16x32_bf16 v[124:127], v[108:111], v[140:143], v[124:127]
	v_mfma_f32_16x16x32_bf16 v[100:103], v[108:111], v[148:151], v[100:103]
	s_setprio 0
	s_barrier
	ds_read_b128 v[104:107], v217
	ds_read_b128 v[108:111], v217 offset:1024
	ds_read_b128 v[136:139], v217 offset:2048
	ds_read_b128 v[140:143], v217 offset:3072
	s_add_u32 s40, s14, 0x10100
	s_addc_u32 s41, s15, 0
	s_mov_b32 m0, s39
	v_lshl_add_u64 v[128:129], s[40:41], 0, v[2:3]
	ds_read_b128 v[144:147], v240 offset:32768
	ds_read_b128 v[148:151], v240 offset:33792
	ds_read_b128 v[176:179], v240 offset:34816
	ds_read_b128 v[180:183], v240 offset:35840
	ds_read_b128 v[184:187], v240 offset:36864
	ds_read_b128 v[188:191], v240 offset:37888
	ds_read_b128 v[192:195], v240 offset:38912
	ds_read_b128 v[196:199], v240 offset:39936
	global_load_lds_dwordx4 v[128:129], off
	v_lshl_add_u64 v[128:129], s[40:41], 0, v[4:5]
	s_mov_b32 m0, s36
	s_nop 0
	global_load_lds_dwordx4 v[128:129], off
	s_waitcnt lgkmcnt(8)
	s_barrier
	s_waitcnt lgkmcnt(0)
	s_setprio 1
	s_waitcnt lgkmcnt(0)
	v_mfma_f32_16x16x32_bf16 v[64:67], v[104:107], v[144:147], v[64:67]
	v_mfma_f32_16x16x32_bf16 v[68:71], v[136:139], v[144:147], v[68:71]
	v_mfma_f32_16x16x32_bf16 v[72:75], v[104:107], v[176:179], v[72:75]
	v_mfma_f32_16x16x32_bf16 v[76:79], v[136:139], v[176:179], v[76:79]
	v_mfma_f32_16x16x32_bf16 v[80:83], v[104:107], v[184:187], v[80:83]
	v_mfma_f32_16x16x32_bf16 v[84:87], v[136:139], v[184:187], v[84:87]
	v_mfma_f32_16x16x32_bf16 v[88:91], v[104:107], v[192:195], v[88:91]
	v_mfma_f32_16x16x32_bf16 v[92:95], v[136:139], v[192:195], v[92:95]
	v_mfma_f32_16x16x32_bf16 v[64:67], v[108:111], v[148:151], v[64:67]
	v_mfma_f32_16x16x32_bf16 v[68:71], v[140:143], v[148:151], v[68:71]
	v_mfma_f32_16x16x32_bf16 v[72:75], v[108:111], v[180:183], v[72:75]
	v_mfma_f32_16x16x32_bf16 v[76:79], v[140:143], v[180:183], v[76:79]
	v_mfma_f32_16x16x32_bf16 v[80:83], v[108:111], v[188:191], v[80:83]
	v_mfma_f32_16x16x32_bf16 v[84:87], v[140:143], v[188:191], v[84:87]
	v_mfma_f32_16x16x32_bf16 v[88:91], v[108:111], v[196:199], v[88:91]
	v_mfma_f32_16x16x32_bf16 v[92:95], v[140:143], v[196:199], v[92:95]
	s_setprio 0
	s_barrier
	s_mov_b32 m0, s38
	v_lshl_add_u64 v[14:15], v[14:15], 0, s[8:9]
	ds_read_b128 v[200:203], v236
	ds_read_b128 v[204:207], v236 offset:1024
	ds_read_b128 v[208:211], v236 offset:2048
	ds_read_b128 v[212:215], v236 offset:3072
	global_load_lds_dwordx4 v[14:15], off
	v_lshl_add_u64 v[12:13], v[12:13], 0, s[8:9]
	s_mov_b32 m0, s37
	s_nop 0
	global_load_lds_dwordx4 v[12:13], off
	s_barrier
	s_waitcnt lgkmcnt(0)
	s_setprio 1
	s_waitcnt lgkmcnt(0)
	v_mfma_f32_16x16x32_bf16 v[12:15], v[200:203], v[144:147], v[112:115]
	v_mfma_f32_16x16x32_bf16 v[32:35], v[208:211], v[144:147], v[32:35]
	v_mfma_f32_16x16x32_bf16 v[36:39], v[200:203], v[176:179], v[36:39]
	v_mfma_f32_16x16x32_bf16 v[40:43], v[208:211], v[176:179], v[40:43]
	v_mfma_f32_16x16x32_bf16 v[44:47], v[200:203], v[184:187], v[44:47]
	v_mfma_f32_16x16x32_bf16 v[48:51], v[208:211], v[184:187], v[48:51]
	v_mfma_f32_16x16x32_bf16 v[52:55], v[200:203], v[192:195], v[52:55]
	v_mfma_f32_16x16x32_bf16 v[56:59], v[208:211], v[192:195], v[56:59]
	v_mfma_f32_16x16x32_bf16 v[12:15], v[204:207], v[148:151], v[12:15]
	v_mfma_f32_16x16x32_bf16 v[32:35], v[212:215], v[148:151], v[32:35]
	v_mfma_f32_16x16x32_bf16 v[36:39], v[204:207], v[180:183], v[36:39]
	v_mfma_f32_16x16x32_bf16 v[40:43], v[212:215], v[180:183], v[40:43]
	v_mfma_f32_16x16x32_bf16 v[44:47], v[204:207], v[188:191], v[44:47]
	v_mfma_f32_16x16x32_bf16 v[48:51], v[212:215], v[188:191], v[48:51]
	v_mfma_f32_16x16x32_bf16 v[52:55], v[204:207], v[196:199], v[52:55]
	v_mfma_f32_16x16x32_bf16 v[56:59], v[212:215], v[196:199], v[56:59]
	s_setprio 0
	s_mov_b32 m0, s34
	v_lshl_add_u64 v[8:9], v[8:9], 0, s[8:9]
	s_barrier
	ds_read_b128 v[112:115], v240 offset:49152
	ds_read_b128 v[144:147], v240 offset:50176
	ds_read_b128 v[148:151], v240 offset:51200
	ds_read_b128 v[176:179], v240 offset:52224
	ds_read_b128 v[180:183], v240 offset:53248
	ds_read_b128 v[184:187], v240 offset:54272
	ds_read_b128 v[188:191], v240 offset:55296
	ds_read_b128 v[192:195], v240 offset:56320
	global_load_lds_dwordx4 v[8:9], off
	v_lshl_add_u64 v[8:9], v[10:11], 0, s[8:9]
	s_mov_b32 m0, s31
	s_nop 0
	global_load_lds_dwordx4 v[8:9], off
	s_barrier
	s_waitcnt lgkmcnt(0)
	s_setprio 1
	s_waitcnt lgkmcnt(0)
	v_mfma_f32_16x16x32_bf16 v[8:11], v[104:107], v[112:115], v[152:155]
	v_mfma_f32_16x16x32_bf16 v[16:19], v[104:107], v[188:191], v[16:19]
	v_mfma_f32_16x16x32_bf16 v[20:23], v[136:139], v[188:191], v[20:23]
	v_mfma_f32_16x16x32_bf16 v[8:11], v[108:111], v[144:147], v[8:11]
	v_mfma_f32_16x16x32_bf16 v[152:155], v[136:139], v[112:115], v[156:159]
	v_mfma_f32_16x16x32_bf16 v[156:159], v[104:107], v[148:151], v[160:163]
	v_mfma_f32_16x16x32_bf16 v[160:163], v[136:139], v[148:151], v[164:167]
	v_mfma_f32_16x16x32_bf16 v[164:167], v[104:107], v[180:183], v[168:171]
	v_mfma_f32_16x16x32_bf16 v[168:171], v[136:139], v[180:183], v[172:175]
	v_mfma_f32_16x16x32_bf16 v[16:19], v[108:111], v[192:195], v[16:19]
	v_mfma_f32_16x16x32_bf16 v[20:23], v[140:143], v[192:195], v[20:23]
	v_mfma_f32_16x16x32_bf16 v[152:155], v[140:143], v[144:147], v[152:155]
	v_mfma_f32_16x16x32_bf16 v[156:159], v[108:111], v[176:179], v[156:159]
	v_mfma_f32_16x16x32_bf16 v[160:163], v[140:143], v[176:179], v[160:163]
	v_mfma_f32_16x16x32_bf16 v[164:167], v[108:111], v[184:187], v[164:167]
	v_mfma_f32_16x16x32_bf16 v[168:171], v[140:143], v[184:187], v[168:171]
	s_setprio 0
	s_barrier
	s_add_u32 s16, s16, 0x10180
	s_addc_u32 s17, s17, 0
	s_mov_b32 m0, s29
	v_lshl_add_u64 v[104:105], s[16:17], 0, v[130:131]
	global_load_lds_dwordx4 v[104:105], off
	v_lshl_add_u64 v[6:7], s[16:17], 0, v[6:7]
	s_mov_b32 m0, s13
	s_nop 0
	global_load_lds_dwordx4 v[6:7], off
	s_waitcnt vmcnt(6)
	s_barrier
	s_setprio 1
	v_mfma_f32_16x16x32_bf16 v[24:27], v[200:203], v[112:115], v[24:27]
	v_mfma_f32_16x16x32_bf16 v[28:31], v[208:211], v[112:115], v[28:31]
	v_mfma_f32_16x16x32_bf16 v[60:63], v[200:203], v[148:151], v[60:63]
	v_mfma_f32_16x16x32_bf16 v[104:107], v[208:211], v[148:151], v[116:119]
	v_mfma_f32_16x16x32_bf16 v[108:111], v[200:203], v[180:183], v[120:123]
	v_mfma_f32_16x16x32_bf16 v[112:115], v[208:211], v[180:183], v[124:127]
	v_mfma_f32_16x16x32_bf16 v[96:99], v[200:203], v[188:191], v[96:99]
	v_mfma_f32_16x16x32_bf16 v[100:103], v[208:211], v[188:191], v[100:103]
	v_mfma_f32_16x16x32_bf16 v[24:27], v[204:207], v[144:147], v[24:27]
	v_mfma_f32_16x16x32_bf16 v[28:31], v[212:215], v[144:147], v[28:31]
	v_mfma_f32_16x16x32_bf16 v[60:63], v[204:207], v[176:179], v[60:63]
	v_mfma_f32_16x16x32_bf16 v[104:107], v[212:215], v[176:179], v[104:107]
	v_mfma_f32_16x16x32_bf16 v[108:111], v[204:207], v[184:187], v[108:111]
	v_mfma_f32_16x16x32_bf16 v[112:115], v[212:215], v[184:187], v[112:115]
	v_mfma_f32_16x16x32_bf16 v[96:99], v[204:207], v[192:195], v[96:99]
	v_mfma_f32_16x16x32_bf16 v[100:103], v[212:215], v[192:195], v[100:103]
	s_setprio 0
	s_add_u32 s14, s14, 0x10180
	s_addc_u32 s15, s15, 0
	s_mov_b32 m0, s30
	v_lshl_add_u64 v[2:3], s[14:15], 0, v[2:3]
	s_barrier
	ds_read_b128 v[116:119], v135
	ds_read_b128 v[120:123], v135 offset:1024
	ds_read_b128 v[124:127], v135 offset:2048
	ds_read_b128 v[136:139], v135 offset:3072
	ds_read_b128 v[140:143], v240
	ds_read_b128 v[144:147], v240 offset:1024
	ds_read_b128 v[148:151], v240 offset:2048
	ds_read_b128 v[172:175], v240 offset:3072
	ds_read_b128 v[176:179], v240 offset:4096
	ds_read_b128 v[180:183], v240 offset:5120
	ds_read_b128 v[184:187], v240 offset:6144
	ds_read_b128 v[188:191], v240 offset:7168
	global_load_lds_dwordx4 v[2:3], off
	v_lshl_add_u64 v[2:3], s[14:15], 0, v[4:5]
	s_mov_b32 m0, s28
	s_nop 0
	global_load_lds_dwordx4 v[2:3], off
	s_barrier
	s_waitcnt lgkmcnt(0)
	s_setprio 1
	s_waitcnt lgkmcnt(0)
	v_mfma_f32_16x16x32_bf16 v[2:5], v[116:119], v[140:143], v[64:67]
	v_mfma_f32_16x16x32_bf16 v[64:67], v[124:127], v[140:143], v[68:71]
	v_mfma_f32_16x16x32_bf16 v[68:71], v[116:119], v[148:151], v[72:75]
	v_mfma_f32_16x16x32_bf16 v[72:75], v[124:127], v[148:151], v[76:79]
	v_mfma_f32_16x16x32_bf16 v[76:79], v[116:119], v[176:179], v[80:83]
	v_mfma_f32_16x16x32_bf16 v[80:83], v[124:127], v[176:179], v[84:87]
	v_mfma_f32_16x16x32_bf16 v[84:87], v[116:119], v[184:187], v[88:91]
	v_mfma_f32_16x16x32_bf16 v[192:195], v[120:123], v[188:191], v[84:87]
	v_mfma_f32_16x16x32_bf16 v[84:87], v[124:127], v[184:187], v[92:95]
	v_mfma_f32_16x16x32_bf16 v[2:5], v[120:123], v[144:147], v[2:5]
	v_mfma_f32_16x16x32_bf16 v[64:67], v[136:139], v[144:147], v[64:67]
	v_mfma_f32_16x16x32_bf16 v[68:71], v[120:123], v[172:175], v[68:71]
	v_mfma_f32_16x16x32_bf16 v[72:75], v[136:139], v[172:175], v[72:75]
	v_mfma_f32_16x16x32_bf16 v[76:79], v[120:123], v[180:183], v[76:79]
	v_mfma_f32_16x16x32_bf16 v[80:83], v[136:139], v[180:183], v[80:83]
	v_mfma_f32_16x16x32_bf16 v[90:93], v[136:139], v[188:191], v[84:87]
	s_setprio 0
	s_barrier
	s_nop 0
	ds_read_b128 v[84:87], v216
	ds_read_b128 v[196:199], v216 offset:1024
	ds_read_b128 v[200:203], v216 offset:2048
	ds_read_b128 v[204:207], v216 offset:3072
	s_barrier
	s_waitcnt lgkmcnt(0)
	s_setprio 1
	s_waitcnt lgkmcnt(0)
	v_mfma_f32_16x16x32_bf16 v[12:15], v[84:87], v[140:143], v[12:15]
	v_mfma_f32_16x16x32_bf16 v[32:35], v[200:203], v[140:143], v[32:35]
	v_mfma_f32_16x16x32_bf16 v[36:39], v[84:87], v[148:151], v[36:39]
	v_mfma_f32_16x16x32_bf16 v[40:43], v[200:203], v[148:151], v[40:43]
	v_mfma_f32_16x16x32_bf16 v[44:47], v[84:87], v[176:179], v[44:47]
	v_mfma_f32_16x16x32_bf16 v[48:51], v[200:203], v[176:179], v[48:51]
	v_mfma_f32_16x16x32_bf16 v[52:55], v[84:87], v[184:187], v[52:55]
	v_mfma_f32_16x16x32_bf16 v[12:15], v[196:199], v[144:147], v[12:15]
	v_mfma_f32_16x16x32_bf16 v[32:35], v[204:207], v[144:147], v[32:35]
	v_mfma_f32_16x16x32_bf16 v[36:39], v[196:199], v[172:175], v[36:39]
	v_mfma_f32_16x16x32_bf16 v[40:43], v[204:207], v[172:175], v[40:43]
	v_mfma_f32_16x16x32_bf16 v[44:47], v[196:199], v[180:183], v[44:47]
	v_mfma_f32_16x16x32_bf16 v[48:51], v[204:207], v[180:183], v[48:51]
	v_mfma_f32_16x16x32_bf16 v[52:55], v[196:199], v[188:191], v[52:55]
	v_mfma_f32_16x16x32_bf16 v[56:59], v[200:203], v[184:187], v[56:59]
	v_mfma_f32_16x16x32_bf16 v[140:143], v[204:207], v[188:191], v[56:59]
	s_setprio 0
	s_barrier
	s_nop 4
	ds_read_b128 v[56:59], v240 offset:16384
	ds_read_b128 v[144:147], v240 offset:17408
	ds_read_b128 v[148:151], v240 offset:18432
	ds_read_b128 v[172:175], v240 offset:19456
	ds_read_b128 v[176:179], v240 offset:20480
	ds_read_b128 v[180:183], v240 offset:21504
	ds_read_b128 v[184:187], v240 offset:22528
	ds_read_b128 v[188:191], v240 offset:23552
	s_waitcnt vmcnt(4)
	s_barrier
	s_waitcnt lgkmcnt(0)
	s_setprio 1
	s_waitcnt lgkmcnt(0)
	v_mfma_f32_16x16x32_bf16 v[6:9], v[116:119], v[56:59], v[8:11]
	v_mfma_f32_16x16x32_bf16 v[16:19], v[116:119], v[184:187], v[16:19]
	v_mfma_f32_16x16x32_bf16 v[6:9], v[120:123], v[144:147], v[6:9]
	v_mfma_f32_16x16x32_bf16 v[152:155], v[124:127], v[56:59], v[152:155]
	v_mfma_f32_16x16x32_bf16 v[156:159], v[116:119], v[148:151], v[156:159]
	v_mfma_f32_16x16x32_bf16 v[160:163], v[124:127], v[148:151], v[160:163]
	v_mfma_f32_16x16x32_bf16 v[164:167], v[116:119], v[176:179], v[164:167]
	v_mfma_f32_16x16x32_bf16 v[168:171], v[124:127], v[176:179], v[168:171]
	v_mfma_f32_16x16x32_bf16 v[16:19], v[120:123], v[188:191], v[16:19]
	v_mfma_f32_16x16x32_bf16 v[20:23], v[124:127], v[184:187], v[20:23]
	v_mfma_f32_16x16x32_bf16 v[152:155], v[136:139], v[144:147], v[152:155]
	v_mfma_f32_16x16x32_bf16 v[156:159], v[120:123], v[172:175], v[156:159]
	v_mfma_f32_16x16x32_bf16 v[160:163], v[136:139], v[172:175], v[160:163]
	v_mfma_f32_16x16x32_bf16 v[164:167], v[120:123], v[180:183], v[164:167]
	v_mfma_f32_16x16x32_bf16 v[168:171], v[136:139], v[180:183], v[168:171]
	v_mfma_f32_16x16x32_bf16 v[136:139], v[136:139], v[188:191], v[20:23]
	s_setprio 0
	s_setprio 1
	v_mfma_f32_16x16x32_bf16 v[20:23], v[84:87], v[56:59], v[24:27]
	v_mfma_f32_16x16x32_bf16 v[208:211], v[196:199], v[144:147], v[20:23]
	v_mfma_f32_16x16x32_bf16 v[20:23], v[200:203], v[56:59], v[28:31]
	v_mfma_f32_16x16x32_bf16 v[26:29], v[204:207], v[144:147], v[20:23]
	v_mfma_f32_16x16x32_bf16 v[20:23], v[84:87], v[148:151], v[60:63]
	v_mfma_f32_16x16x32_bf16 v[144:147], v[196:199], v[172:175], v[20:23]
	v_mfma_f32_16x16x32_bf16 v[20:23], v[200:203], v[148:151], v[104:107]
	v_mfma_f32_16x16x32_bf16 v[148:151], v[204:207], v[172:175], v[20:23]
	v_mfma_f32_16x16x32_bf16 v[20:23], v[84:87], v[176:179], v[108:111]
	v_mfma_f32_16x16x32_bf16 v[172:175], v[196:199], v[180:183], v[20:23]
	v_mfma_f32_16x16x32_bf16 v[20:23], v[200:203], v[176:179], v[112:115]
	v_mfma_f32_16x16x32_bf16 v[176:179], v[204:207], v[180:183], v[20:23]
	v_mfma_f32_16x16x32_bf16 v[20:23], v[84:87], v[184:187], v[96:99]
	v_mfma_f32_16x16x32_bf16 v[180:183], v[196:199], v[188:191], v[20:23]
	v_mfma_f32_16x16x32_bf16 v[20:23], v[200:203], v[184:187], v[100:103]
	v_mfma_f32_16x16x32_bf16 v[184:187], v[204:207], v[188:191], v[20:23]
	s_setprio 0
	s_barrier
	ds_read_b128 v[188:191], v217
	ds_read_b128 v[196:199], v217 offset:1024
	ds_read_b128 v[200:203], v217 offset:2048
	ds_read_b128 v[204:207], v217 offset:3072
	s_nop 0
	ds_read_b128 v[20:23], v240 offset:32768
	ds_read_b128 v[94:97], v240 offset:33792
	ds_read_b128 v[106:109], v240 offset:34816
	ds_read_b128 v[212:215], v240 offset:35840
	ds_read_b128 v[216:219], v240 offset:36864
	ds_read_b128 v[220:223], v240 offset:37888
	ds_read_b128 v[224:227], v240 offset:38912
	ds_read_b128 v[228:231], v240 offset:39936
	s_waitcnt vmcnt(2)
	s_barrier
	s_waitcnt lgkmcnt(0)
	s_setprio 1
	s_waitcnt lgkmcnt(0)
	v_mfma_f32_16x16x32_bf16 v[2:5], v[188:191], v[20:23], v[2:5]
	v_mfma_f32_16x16x32_bf16 v[122:125], v[196:199], v[94:97], v[2:5]
	v_mfma_f32_16x16x32_bf16 v[2:5], v[200:203], v[20:23], v[64:67]
	v_mfma_f32_16x16x32_bf16 v[114:117], v[204:207], v[94:97], v[2:5]
	v_mfma_f32_16x16x32_bf16 v[2:5], v[188:191], v[106:109], v[68:71]
	v_mfma_f32_16x16x32_bf16 v[102:105], v[196:199], v[212:215], v[2:5]
	v_mfma_f32_16x16x32_bf16 v[2:5], v[200:203], v[106:109], v[72:75]
	v_mfma_f32_16x16x32_bf16 v[98:101], v[204:207], v[212:215], v[2:5]
	v_mfma_f32_16x16x32_bf16 v[2:5], v[188:191], v[216:219], v[76:79]
	v_mfma_f32_16x16x32_bf16 v[86:89], v[196:199], v[220:223], v[2:5]
	v_mfma_f32_16x16x32_bf16 v[2:5], v[200:203], v[216:219], v[80:83]
	v_mfma_f32_16x16x32_bf16 v[82:85], v[204:207], v[220:223], v[2:5]
	v_mfma_f32_16x16x32_bf16 v[2:5], v[188:191], v[224:227], v[192:195]
	v_mfma_f32_16x16x32_bf16 v[70:73], v[196:199], v[228:231], v[2:5]
	v_mfma_f32_16x16x32_bf16 v[2:5], v[200:203], v[224:227], v[90:93]
	v_mfma_f32_16x16x32_bf16 v[58:61], v[204:207], v[228:231], v[2:5]
	s_setprio 0
	s_barrier
	s_nop 4
	ds_read_b128 v[2:5], v236
	ds_read_b128 v[192:195], v236 offset:1024
	ds_read_b128 v[232:235], v236 offset:2048
	ds_read_b128 v[236:239], v236 offset:3072
	s_waitcnt vmcnt(0)
	s_barrier
	s_waitcnt lgkmcnt(0)
	s_setprio 1
	s_waitcnt lgkmcnt(0)
	v_mfma_f32_16x16x32_bf16 v[10:13], v[2:5], v[20:23], v[12:15]
	v_mfma_f32_16x16x32_bf16 v[126:129], v[192:195], v[94:97], v[10:13]
	v_mfma_f32_16x16x32_bf16 v[10:13], v[232:235], v[20:23], v[32:35]
	v_mfma_f32_16x16x32_bf16 v[118:121], v[236:239], v[94:97], v[10:13]
	v_mfma_f32_16x16x32_bf16 v[10:13], v[2:5], v[106:109], v[36:39]
	v_mfma_f32_16x16x32_bf16 v[110:113], v[192:195], v[212:215], v[10:13]
	v_mfma_f32_16x16x32_bf16 v[10:13], v[232:235], v[106:109], v[40:43]
	v_mfma_f32_16x16x32_bf16 v[106:109], v[236:239], v[212:215], v[10:13]
	v_mfma_f32_16x16x32_bf16 v[10:13], v[2:5], v[216:219], v[44:47]
	v_mfma_f32_16x16x32_bf16 v[94:97], v[192:195], v[220:223], v[10:13]
	v_mfma_f32_16x16x32_bf16 v[10:13], v[232:235], v[216:219], v[48:51]
	v_mfma_f32_16x16x32_bf16 v[90:93], v[236:239], v[220:223], v[10:13]
	v_mfma_f32_16x16x32_bf16 v[10:13], v[2:5], v[224:227], v[52:55]
	v_mfma_f32_16x16x32_bf16 v[78:81], v[192:195], v[228:231], v[10:13]
	v_mfma_f32_16x16x32_bf16 v[10:13], v[232:235], v[224:227], v[140:143]
	v_mfma_f32_16x16x32_bf16 v[74:77], v[236:239], v[228:231], v[10:13]
	s_setprio 0
	s_barrier
	s_nop 4
	ds_read_b128 v[10:13], v240 offset:49152
	ds_read_b128 v[34:37], v240 offset:50176
	ds_read_b128 v[140:143], v240 offset:51200
	ds_read_b128 v[212:215], v240 offset:52224
	ds_read_b128 v[216:219], v240 offset:53248
	ds_read_b128 v[220:223], v240 offset:54272
	ds_read_b128 v[224:227], v240 offset:55296
	ds_read_b128 v[228:231], v240 offset:56320
	s_barrier
	s_waitcnt lgkmcnt(0)
	s_setprio 1
	s_waitcnt lgkmcnt(0)
	v_mfma_f32_16x16x32_bf16 v[6:9], v[188:191], v[10:13], v[6:9]
	v_mfma_f32_16x16x32_bf16 v[66:69], v[196:199], v[34:37], v[6:9]
	v_mfma_f32_16x16x32_bf16 v[6:9], v[200:203], v[10:13], v[152:155]
	v_mfma_f32_16x16x32_bf16 v[54:57], v[204:207], v[34:37], v[6:9]
	v_mfma_f32_16x16x32_bf16 v[6:9], v[188:191], v[140:143], v[156:159]
	v_mfma_f32_16x16x32_bf16 v[46:49], v[196:199], v[212:215], v[6:9]
	v_mfma_f32_16x16x32_bf16 v[6:9], v[200:203], v[140:143], v[160:163]
	v_mfma_f32_16x16x32_bf16 v[38:41], v[204:207], v[212:215], v[6:9]
	v_mfma_f32_16x16x32_bf16 v[6:9], v[188:191], v[216:219], v[164:167]
	v_mfma_f32_16x16x32_bf16 v[30:33], v[196:199], v[220:223], v[6:9]
	v_mfma_f32_16x16x32_bf16 v[6:9], v[200:203], v[216:219], v[168:171]
	v_mfma_f32_16x16x32_bf16 v[22:25], v[204:207], v[220:223], v[6:9]
	v_mfma_f32_16x16x32_bf16 v[6:9], v[188:191], v[224:227], v[16:19]
	v_mfma_f32_16x16x32_bf16 v[14:17], v[196:199], v[228:231], v[6:9]
	v_mfma_f32_16x16x32_bf16 v[6:9], v[200:203], v[224:227], v[136:139]
	v_mfma_f32_16x16x32_bf16 v[6:9], v[204:207], v[228:231], v[6:9]
	s_setprio 0
	s_setprio 1
	v_mfma_f32_16x16x32_bf16 v[18:21], v[2:5], v[10:13], v[208:211]
	v_mfma_f32_16x16x32_bf16 v[10:13], v[232:235], v[10:13], v[26:29]
	v_mfma_f32_16x16x32_bf16 v[50:53], v[236:239], v[34:37], v[10:13]
	v_mfma_f32_16x16x32_bf16 v[10:13], v[2:5], v[140:143], v[144:147]
	v_mfma_f32_16x16x32_bf16 v[42:45], v[192:195], v[212:215], v[10:13]
	v_mfma_f32_16x16x32_bf16 v[10:13], v[232:235], v[140:143], v[148:151]
	v_mfma_f32_16x16x32_bf16 v[62:65], v[192:195], v[34:37], v[18:21]
	v_mfma_f32_16x16x32_bf16 v[34:37], v[236:239], v[212:215], v[10:13]
	v_mfma_f32_16x16x32_bf16 v[10:13], v[2:5], v[216:219], v[172:175]
	v_mfma_f32_16x16x32_bf16 v[26:29], v[192:195], v[220:223], v[10:13]
	v_mfma_f32_16x16x32_bf16 v[10:13], v[232:235], v[216:219], v[176:179]
	v_mfma_f32_16x16x32_bf16 v[2:5], v[2:5], v[224:227], v[180:183]
	v_mfma_f32_16x16x32_bf16 v[18:21], v[236:239], v[220:223], v[10:13]
	v_mfma_f32_16x16x32_bf16 v[10:13], v[192:195], v[228:231], v[2:5]
	v_mfma_f32_16x16x32_bf16 v[2:5], v[232:235], v[224:227], v[184:187]
	v_mfma_f32_16x16x32_bf16 v[2:5], v[236:239], v[228:231], v[2:5]
	s_setprio 0
	s_cmpk_gt_u32 s27, 0xff
	s_barrier
	s_cbranch_scc1 .LBB0_122
	s_barrier
	s_branch .LBB0_122
